# memory cross-attention: one head per workgroup, K and V^T tiles staged once per workgroup through LDS by LDS-DMA (4-stage ring, one barrier per tile) instead of per-wave L2 loads
# speedup vs baseline: 1.0093x; 1.0093x over previous
; __device__ __forceinline__ f32x4 mfma16(bf16x8 a, bf16x8 b, f32x4 c) { return __builtin_amdgcn_mfma_f32_16x16x32_bf16(a, b, c, 0, 0, 0); }
; __device__ __forceinline__ void mem_task(bf16_t* zb, const bf16_t* kvm_b, const bf16_t* vmt_b, int hm, int t0, int lane, bool do_store) {
;     const int n = lane & 15, fq = lane >> 4;
;     bf16_t* qp = zb + (size_t)(t0 + n) * ZM + ZC_QM + hm * 256;
;     bf16x8 qf[8];
; #pragma unroll
;     for (int kk = 0; kk < 8; ++kk) qf[kk] = *(const bf16x8*)(qp + kk * 32 + 8 * fq);
;     f32x4 zero4 = {0.f, 0.f, 0.f, 0.f}; asm volatile("" : "+v"(zero4));
;     f32x4 s[16];
;     const bf16_t* kbase = kvm_b + (size_t)(8 * (n >> 2) + (n & 3)) * 2048 + hm * 256 + 8 * fq;
;     bf16x8 kfr[3][8];
; #pragma unroll
;     for (int kk = 0; kk < 8; ++kk) kfr[0][kk] = *(const bf16x8*)(kbase + kk * 32);
;     { const bf16_t* kp = kbase + (size_t)4 * 2048;
; #pragma unroll
;       for (int kk = 0; kk < 8; ++kk) kfr[1][kk] = *(const bf16x8*)(kp + kk * 32); }
; #pragma unroll
;     for (int kt = 0; kt < 16; ++kt) {
;         if (kt + 2 < 16) { const bf16_t* kp = kbase + (size_t)(((kt + 2) >> 1) * 32 + 4 * ((kt + 2) & 1)) * 2048;
; #pragma unroll
;             for (int kk = 0; kk < 8; ++kk) kfr[(kt + 2) % 3][kk] = *(const bf16x8*)(kp + kk * 32); }
;         f32x4 acc = zero4;
;         __builtin_amdgcn_s_setprio(1);
; #pragma unroll
;         for (int kk = 0; kk < 8; ++kk) acc = mfma16(kfr[kt % 3][kk], qf[kk], acc);
;         __builtin_amdgcn_s_setprio(0);
;         s[kt] = acc; }
; __global__ void __launch_bounds__(512, 2) mega(Args a) {
;     ...
;             for (int prep_ = 0; prep_ < PROBE_C2; ++prep_) for (int it = gw; it < (SEQ / 16) * 4; it += NGW) { const int hm = it & 3, t0 = (it >> 2) * 16;
;                 mem_task(ZMAIN, KVM + (size_t)b * 256 * 2048, VMT + (size_t)b * 4 * 256 * 256, hm, t0, lane, prep_ == PROBE_C2 - 1); }
.LBB0_364:
	s_cmpk_gt_i32 s62, 0x7ff
	s_mov_b32 s8, 0x14000
	s_movk_i32 s9, 0x4000
	s_mov_b32 s10, 0x8000
	s_movk_i32 s11, 0x3600
	s_mov_b32 s12, 0x40000
	s_mov_b32 s13, 0x20000
	s_mov_b32 s14, 0x60000
	s_mov_b64 s[16:17], 0x1000
	s_cbranch_scc1 .LBB0_367
	v_readlane_b32 s2, v254, 30
	s_lshl_b32 s0, s2, 19
	s_add_u32 s4, s68, 0x5300000
	s_addc_u32 s5, s69, 0
	s_add_u32 s0, s4, s0
	v_and_b32_e32 v1, 3, v204
	s_addc_u32 s1, s5, 0
	s_lshl_b32 s2, s2, 19
	v_and_or_b32 v0, v0, 24, v1
	s_add_u32 s2, s70, s2
	v_mov_b32_e32 v0, 0
	v_mov_b32_e32 v1, v64
	s_addc_u32 s3, s71, 0
	v_lshrrev_b32_e32 v3, 4, v204
	v_lshl_add_u64 v[0:1], s[0:1], 0, v[0:1]
	v_lshl_add_u32 v4, v204, 4, v233
	v_mov_b32_e32 v5, v64
	v_lshlrev_b32_e32 v2, 3, v3
	v_lshl_add_u64 v[66:67], v[0:1], 0, v[4:5]
	v_lshl_add_u64 v[140:141], s[2:3], 0, v[4:5]
	v_lshlrev_b32_e32 v0, 2, v3
	s_lshl_b32 s0, s60, 5
	s_lshl_b32 s1, s89, 2
	s_lshl_b32 s2, s60, 11
	s_lshl_b32 s3, s89, 8
	v_and_b32_e32 v65, 15, v204
	s_add_i32 s0, s0, s1
	s_lshl_b32 s1, s35, 5
	s_add_i32 s3, s2, s3
	s_lshl_b32 s4, s35, 11
	v_lshlrev_b32_e32 v142, 1, v2
	v_lshlrev_b32_e32 v144, 1, v0
	s_mov_b32 s5, s62
	s_lshr_b32 s0, s60, 2
	s_lshl_b32 s0, s0, 7
	s_lshl_b32 s6, s89, 4
	s_add_i32 s0, s0, s6
	s_and_b32 s3, s60, 3
	s_lshl_b32 s3, s3, 8
.LBB0_366:
	v_and_or_b32 v186, s0, -16, v65
	v_mov_b64_e32 v[188:189], s[78:79]
	s_and_b32 s2, s3, 0x300
	v_mad_i64_i32 v[188:189], s[6:7], v186, s11, v[188:189]
	s_lshl_b32 s38, s2, 1
	v_lshl_add_u64 v[188:189], v[188:189], 0, s[38:39]
	v_lshl_add_u64 v[184:185], v[188:189], 0, s[16:17]
	v_mov_b32_e32 v143, v64
	v_mov_b32_e32 v145, v64
	v_lshl_add_u64 v[188:189], v[184:185], 0, v[142:143]
	global_load_dwordx4 v[0:3], v[188:189], off
	global_load_dwordx4 v[4:7], v[188:189], off offset:64
	global_load_dwordx4 v[8:11], v[188:189], off offset:128
	global_load_dwordx4 v[12:15], v[188:189], off offset:192
	global_load_dwordx4 v[16:19], v[188:189], off offset:256
	global_load_dwordx4 v[20:23], v[188:189], off offset:320
	global_load_dwordx4 v[24:27], v[188:189], off offset:384
	global_load_dwordx4 v[28:31], v[188:189], off offset:448
	v_lshl_add_u64 v[184:185], v[184:185], 0, v[144:145]
	s_lshl_b32 s98, s2, 9
	s_mov_b32 s99, 0
	v_lshl_add_u64 v[180:181], v[66:67], 0, s[98:99]
	v_lshl_add_u64 v[182:183], v[140:141], 0, s[98:99]
	s_lshl_b32 s7, s89, 10
	s_sub_u32 s98, s7, 0x1000
	s_subb_u32 s99, 0, 0
	v_lshl_add_u64 v[180:181], v[180:181], 0, s[98:99]
	v_lshl_add_u64 v[182:183], v[182:183], 0, s[98:99]
	v_lshlrev_b32_e32 v178, 4, v204
	s_mov_b64 s[98:99], 0x2000
	s_add_i32 m0, s7, 0
	s_nop 0
	global_load_lds_dwordx4 v[180:181], off
	v_lshl_add_u64 v[180:181], v[180:181], 0, s[98:99]
	s_add_i32 m0, s7, 8192
	s_nop 0
	global_load_lds_dwordx4 v[180:181], off
	v_lshl_add_u64 v[180:181], v[180:181], 0, s[98:99]
	s_add_i32 m0, s7, 16384
	s_nop 0
	global_load_lds_dwordx4 v[180:181], off
	v_lshl_add_u64 v[180:181], v[180:181], 0, s[98:99]
	s_waitcnt vmcnt(2)
	s_barrier
	ds_read_b128 v[104:107], v178 offset:0
	ds_read_b128 v[108:111], v178 offset:1024
	ds_read_b128 v[112:115], v178 offset:2048
	ds_read_b128 v[116:119], v178 offset:3072
	ds_read_b128 v[120:123], v178 offset:4096
	ds_read_b128 v[124:127], v178 offset:5120
	ds_read_b128 v[128:131], v178 offset:6144
	ds_read_b128 v[132:135], v178 offset:7168
	s_waitcnt vmcnt(1)
	s_barrier
	s_add_i32 m0, s7, 24576
	s_nop 0
	global_load_lds_dwordx4 v[180:181], off
	v_lshl_add_u64 v[180:181], v[180:181], 0, s[98:99]
	ds_read_b128 v[146:149], v178 offset:8192
	ds_read_b128 v[150:153], v178 offset:9216
	ds_read_b128 v[154:157], v178 offset:10240
	ds_read_b128 v[158:161], v178 offset:11264
	ds_read_b128 v[162:165], v178 offset:12288
	ds_read_b128 v[166:169], v178 offset:13312
	ds_read_b128 v[170:173], v178 offset:14336
	ds_read_b128 v[174:177], v178 offset:15360
	s_waitcnt lgkmcnt(8)
	v_mfma_f32_16x16x32_bf16 v[32:35], v[104:107], v[0:3], 0
	v_mfma_f32_16x16x32_bf16 v[32:35], v[108:111], v[4:7], v[32:35]
	v_mfma_f32_16x16x32_bf16 v[32:35], v[112:115], v[8:11], v[32:35]
	v_mfma_f32_16x16x32_bf16 v[32:35], v[116:119], v[12:15], v[32:35]
	v_mfma_f32_16x16x32_bf16 v[32:35], v[120:123], v[16:19], v[32:35]
	v_mfma_f32_16x16x32_bf16 v[32:35], v[124:127], v[20:23], v[32:35]
	v_mfma_f32_16x16x32_bf16 v[32:35], v[128:131], v[24:27], v[32:35]
	v_mfma_f32_16x16x32_bf16 v[32:35], v[132:135], v[28:31], v[32:35]
	s_waitcnt vmcnt(1)
	s_barrier
	s_add_i32 m0, s7, 0
	s_nop 0
	global_load_lds_dwordx4 v[180:181], off
	v_lshl_add_u64 v[180:181], v[180:181], 0, s[98:99]
	ds_read_b128 v[104:107], v178 offset:16384
	ds_read_b128 v[108:111], v178 offset:17408
	ds_read_b128 v[112:115], v178 offset:18432
	ds_read_b128 v[116:119], v178 offset:19456
	ds_read_b128 v[120:123], v178 offset:20480
	ds_read_b128 v[124:127], v178 offset:21504
	ds_read_b128 v[128:131], v178 offset:22528
	ds_read_b128 v[132:135], v178 offset:23552
	s_waitcnt lgkmcnt(8)
	v_mfma_f32_16x16x32_bf16 v[36:39], v[146:149], v[0:3], 0
	v_mfma_f32_16x16x32_bf16 v[36:39], v[150:153], v[4:7], v[36:39]
	v_mfma_f32_16x16x32_bf16 v[36:39], v[154:157], v[8:11], v[36:39]
	v_mfma_f32_16x16x32_bf16 v[36:39], v[158:161], v[12:15], v[36:39]
	v_mfma_f32_16x16x32_bf16 v[36:39], v[162:165], v[16:19], v[36:39]
	v_mfma_f32_16x16x32_bf16 v[36:39], v[166:169], v[20:23], v[36:39]
	v_mfma_f32_16x16x32_bf16 v[36:39], v[170:173], v[24:27], v[36:39]
	v_mfma_f32_16x16x32_bf16 v[36:39], v[174:177], v[28:31], v[36:39]
	s_waitcnt vmcnt(1)
	s_barrier
; __device__ __forceinline__ f32x4 mfma16(bf16x8 a, bf16x8 b, f32x4 c) { return __builtin_amdgcn_mfma_f32_16x16x32_bf16(a, b, c, 0, 0, 0); }
; __device__ __forceinline__ void mem_task(bf16_t* zb, const bf16_t* kvm_b, const bf16_t* vmt_b, int hm, int t0, int lane, bool do_store) {
;     ...
;     for (int kt = 0; kt < 16; ++kt) {
;         if (kt + 2 < 16) { const bf16_t* kp = kbase + (size_t)(((kt + 2) >> 1) * 32 + 4 * ((kt + 2) & 1)) * 2048;
; #pragma unroll
;             for (int kk = 0; kk < 8; ++kk) kfr[(kt + 2) % 3][kk] = *(const bf16x8*)(kp + kk * 32); }
;         f32x4 acc = zero4;
;         __builtin_amdgcn_s_setprio(1);
; #pragma unroll
;         for (int kk = 0; kk < 8; ++kk) acc = mfma16(kfr[kt % 3][kk], qf[kk], acc);
;         __builtin_amdgcn_s_setprio(0);
;         s[kt] = acc; }
	s_add_i32 m0, s7, 8192
	s_nop 0
	global_load_lds_dwordx4 v[180:181], off
	v_lshl_add_u64 v[180:181], v[180:181], 0, s[98:99]
	ds_read_b128 v[146:149], v178 offset:24576
	ds_read_b128 v[150:153], v178 offset:25600
	ds_read_b128 v[154:157], v178 offset:26624
	ds_read_b128 v[158:161], v178 offset:27648
	ds_read_b128 v[162:165], v178 offset:28672
	ds_read_b128 v[166:169], v178 offset:29696
	ds_read_b128 v[170:173], v178 offset:30720
	ds_read_b128 v[174:177], v178 offset:31744
	s_waitcnt lgkmcnt(8)
	v_mfma_f32_16x16x32_bf16 v[40:43], v[104:107], v[0:3], 0
	v_mfma_f32_16x16x32_bf16 v[40:43], v[108:111], v[4:7], v[40:43]
	v_mfma_f32_16x16x32_bf16 v[40:43], v[112:115], v[8:11], v[40:43]
	v_mfma_f32_16x16x32_bf16 v[40:43], v[116:119], v[12:15], v[40:43]
	v_mfma_f32_16x16x32_bf16 v[40:43], v[120:123], v[16:19], v[40:43]
	v_mfma_f32_16x16x32_bf16 v[40:43], v[124:127], v[20:23], v[40:43]
	v_mfma_f32_16x16x32_bf16 v[40:43], v[128:131], v[24:27], v[40:43]
	v_mfma_f32_16x16x32_bf16 v[40:43], v[132:135], v[28:31], v[40:43]
	s_waitcnt vmcnt(1)
	s_barrier
	s_add_i32 m0, s7, 16384
	s_nop 0
	global_load_lds_dwordx4 v[180:181], off
	v_lshl_add_u64 v[180:181], v[180:181], 0, s[98:99]
	ds_read_b128 v[104:107], v178 offset:0
	ds_read_b128 v[108:111], v178 offset:1024
	ds_read_b128 v[112:115], v178 offset:2048
	ds_read_b128 v[116:119], v178 offset:3072
	ds_read_b128 v[120:123], v178 offset:4096
	ds_read_b128 v[124:127], v178 offset:5120
	ds_read_b128 v[128:131], v178 offset:6144
	ds_read_b128 v[132:135], v178 offset:7168
	s_waitcnt lgkmcnt(8)
	v_mfma_f32_16x16x32_bf16 v[44:47], v[146:149], v[0:3], 0
	v_mfma_f32_16x16x32_bf16 v[44:47], v[150:153], v[4:7], v[44:47]
	v_mfma_f32_16x16x32_bf16 v[44:47], v[154:157], v[8:11], v[44:47]
	v_mfma_f32_16x16x32_bf16 v[44:47], v[158:161], v[12:15], v[44:47]
	v_mfma_f32_16x16x32_bf16 v[44:47], v[162:165], v[16:19], v[44:47]
	v_mfma_f32_16x16x32_bf16 v[44:47], v[166:169], v[20:23], v[44:47]
	v_mfma_f32_16x16x32_bf16 v[44:47], v[170:173], v[24:27], v[44:47]
	v_mfma_f32_16x16x32_bf16 v[44:47], v[174:177], v[28:31], v[44:47]
	s_waitcnt vmcnt(1)
	s_barrier
	s_add_i32 m0, s7, 24576
	s_nop 0
	global_load_lds_dwordx4 v[180:181], off
	v_lshl_add_u64 v[180:181], v[180:181], 0, s[98:99]
	ds_read_b128 v[146:149], v178 offset:8192
	ds_read_b128 v[150:153], v178 offset:9216
	ds_read_b128 v[154:157], v178 offset:10240
	ds_read_b128 v[158:161], v178 offset:11264
	ds_read_b128 v[162:165], v178 offset:12288
	ds_read_b128 v[166:169], v178 offset:13312
	ds_read_b128 v[170:173], v178 offset:14336
	ds_read_b128 v[174:177], v178 offset:15360
	s_waitcnt lgkmcnt(8)
	v_mfma_f32_16x16x32_bf16 v[48:51], v[104:107], v[0:3], 0
	v_mfma_f32_16x16x32_bf16 v[48:51], v[108:111], v[4:7], v[48:51]
	v_mfma_f32_16x16x32_bf16 v[48:51], v[112:115], v[8:11], v[48:51]
	v_mfma_f32_16x16x32_bf16 v[48:51], v[116:119], v[12:15], v[48:51]
	v_mfma_f32_16x16x32_bf16 v[48:51], v[120:123], v[16:19], v[48:51]
	v_mfma_f32_16x16x32_bf16 v[48:51], v[124:127], v[20:23], v[48:51]
	v_mfma_f32_16x16x32_bf16 v[48:51], v[128:131], v[24:27], v[48:51]
	v_mfma_f32_16x16x32_bf16 v[48:51], v[132:135], v[28:31], v[48:51]
	s_waitcnt vmcnt(1)
	s_barrier
	s_add_i32 m0, s7, 0
	s_nop 0
	global_load_lds_dwordx4 v[180:181], off
	v_lshl_add_u64 v[180:181], v[180:181], 0, s[98:99]
	ds_read_b128 v[104:107], v178 offset:16384
	ds_read_b128 v[108:111], v178 offset:17408
	ds_read_b128 v[112:115], v178 offset:18432
	ds_read_b128 v[116:119], v178 offset:19456
	ds_read_b128 v[120:123], v178 offset:20480
	ds_read_b128 v[124:127], v178 offset:21504
	ds_read_b128 v[128:131], v178 offset:22528
	ds_read_b128 v[132:135], v178 offset:23552
	s_waitcnt lgkmcnt(8)
	v_mfma_f32_16x16x32_bf16 v[52:55], v[146:149], v[0:3], 0
	v_mfma_f32_16x16x32_bf16 v[52:55], v[150:153], v[4:7], v[52:55]
	v_mfma_f32_16x16x32_bf16 v[52:55], v[154:157], v[8:11], v[52:55]
	v_mfma_f32_16x16x32_bf16 v[52:55], v[158:161], v[12:15], v[52:55]
	v_mfma_f32_16x16x32_bf16 v[52:55], v[162:165], v[16:19], v[52:55]
	v_mfma_f32_16x16x32_bf16 v[52:55], v[166:169], v[20:23], v[52:55]
	v_mfma_f32_16x16x32_bf16 v[52:55], v[170:173], v[24:27], v[52:55]
	v_mfma_f32_16x16x32_bf16 v[52:55], v[174:177], v[28:31], v[52:55]
	s_waitcnt vmcnt(1)
	s_barrier
	s_add_i32 m0, s7, 8192
	s_nop 0
	global_load_lds_dwordx4 v[180:181], off
	v_lshl_add_u64 v[180:181], v[180:181], 0, s[98:99]
	ds_read_b128 v[146:149], v178 offset:24576
	ds_read_b128 v[150:153], v178 offset:25600
	ds_read_b128 v[154:157], v178 offset:26624
	ds_read_b128 v[158:161], v178 offset:27648
	ds_read_b128 v[162:165], v178 offset:28672
	ds_read_b128 v[166:169], v178 offset:29696
	ds_read_b128 v[170:173], v178 offset:30720
	ds_read_b128 v[174:177], v178 offset:31744
	s_waitcnt lgkmcnt(8)
	v_mfma_f32_16x16x32_bf16 v[56:59], v[104:107], v[0:3], 0
	v_mfma_f32_16x16x32_bf16 v[56:59], v[108:111], v[4:7], v[56:59]
	v_mfma_f32_16x16x32_bf16 v[56:59], v[112:115], v[8:11], v[56:59]
	v_mfma_f32_16x16x32_bf16 v[56:59], v[116:119], v[12:15], v[56:59]
	v_mfma_f32_16x16x32_bf16 v[56:59], v[120:123], v[16:19], v[56:59]
	v_mfma_f32_16x16x32_bf16 v[56:59], v[124:127], v[20:23], v[56:59]
	v_mfma_f32_16x16x32_bf16 v[56:59], v[128:131], v[24:27], v[56:59]
	v_mfma_f32_16x16x32_bf16 v[56:59], v[132:135], v[28:31], v[56:59]
	s_waitcnt vmcnt(1)
	s_barrier
; __device__ __forceinline__ f32x4 mfma16(bf16x8 a, bf16x8 b, f32x4 c) { return __builtin_amdgcn_mfma_f32_16x16x32_bf16(a, b, c, 0, 0, 0); }
; __device__ __forceinline__ void mem_task(bf16_t* zb, const bf16_t* kvm_b, const bf16_t* vmt_b, int hm, int t0, int lane, bool do_store) {
;     ...
;     for (int kt = 0; kt < 16; ++kt) {
;         if (kt + 2 < 16) { const bf16_t* kp = kbase + (size_t)(((kt + 2) >> 1) * 32 + 4 * ((kt + 2) & 1)) * 2048;
; #pragma unroll
;             for (int kk = 0; kk < 8; ++kk) kfr[(kt + 2) % 3][kk] = *(const bf16x8*)(kp + kk * 32); }
;         f32x4 acc = zero4;
;         __builtin_amdgcn_s_setprio(1);
; #pragma unroll
;         for (int kk = 0; kk < 8; ++kk) acc = mfma16(kfr[kt % 3][kk], qf[kk], acc);
;         __builtin_amdgcn_s_setprio(0);
;         s[kt] = acc; }
	s_add_i32 m0, s7, 16384
	s_nop 0
	global_load_lds_dwordx4 v[180:181], off
	v_lshl_add_u64 v[180:181], v[180:181], 0, s[98:99]
	ds_read_b128 v[104:107], v178 offset:0
	ds_read_b128 v[108:111], v178 offset:1024
	ds_read_b128 v[112:115], v178 offset:2048
	ds_read_b128 v[116:119], v178 offset:3072
	ds_read_b128 v[120:123], v178 offset:4096
	ds_read_b128 v[124:127], v178 offset:5120
	ds_read_b128 v[128:131], v178 offset:6144
	ds_read_b128 v[132:135], v178 offset:7168
	s_waitcnt lgkmcnt(8)
	v_mfma_f32_16x16x32_bf16 v[60:63], v[146:149], v[0:3], 0
	v_mfma_f32_16x16x32_bf16 v[60:63], v[150:153], v[4:7], v[60:63]
	v_mfma_f32_16x16x32_bf16 v[60:63], v[154:157], v[8:11], v[60:63]
	v_mfma_f32_16x16x32_bf16 v[60:63], v[158:161], v[12:15], v[60:63]
	v_mfma_f32_16x16x32_bf16 v[60:63], v[162:165], v[16:19], v[60:63]
	v_mfma_f32_16x16x32_bf16 v[60:63], v[166:169], v[20:23], v[60:63]
	v_mfma_f32_16x16x32_bf16 v[60:63], v[170:173], v[24:27], v[60:63]
	v_mfma_f32_16x16x32_bf16 v[60:63], v[174:177], v[28:31], v[60:63]
	s_waitcnt vmcnt(1)
	s_barrier
	s_add_i32 m0, s7, 24576
	s_nop 0
	global_load_lds_dwordx4 v[180:181], off
	v_lshl_add_u64 v[180:181], v[180:181], 0, s[98:99]
	ds_read_b128 v[146:149], v178 offset:8192
	ds_read_b128 v[150:153], v178 offset:9216
	ds_read_b128 v[154:157], v178 offset:10240
	ds_read_b128 v[158:161], v178 offset:11264
	ds_read_b128 v[162:165], v178 offset:12288
	ds_read_b128 v[166:169], v178 offset:13312
	ds_read_b128 v[170:173], v178 offset:14336
	ds_read_b128 v[174:177], v178 offset:15360
	s_waitcnt lgkmcnt(8)
	v_mfma_f32_16x16x32_bf16 v[72:75], v[104:107], v[0:3], 0
	v_mfma_f32_16x16x32_bf16 v[72:75], v[108:111], v[4:7], v[72:75]
	v_mfma_f32_16x16x32_bf16 v[72:75], v[112:115], v[8:11], v[72:75]
	v_mfma_f32_16x16x32_bf16 v[72:75], v[116:119], v[12:15], v[72:75]
	v_mfma_f32_16x16x32_bf16 v[72:75], v[120:123], v[16:19], v[72:75]
	v_mfma_f32_16x16x32_bf16 v[72:75], v[124:127], v[20:23], v[72:75]
	v_mfma_f32_16x16x32_bf16 v[72:75], v[128:131], v[24:27], v[72:75]
	v_mfma_f32_16x16x32_bf16 v[72:75], v[132:135], v[28:31], v[72:75]
	s_waitcnt vmcnt(1)
	s_barrier
	s_add_i32 m0, s7, 0
	s_nop 0
	global_load_lds_dwordx4 v[180:181], off
	v_lshl_add_u64 v[180:181], v[180:181], 0, s[98:99]
	ds_read_b128 v[104:107], v178 offset:16384
	ds_read_b128 v[108:111], v178 offset:17408
	ds_read_b128 v[112:115], v178 offset:18432
	ds_read_b128 v[116:119], v178 offset:19456
	ds_read_b128 v[120:123], v178 offset:20480
	ds_read_b128 v[124:127], v178 offset:21504
	ds_read_b128 v[128:131], v178 offset:22528
	ds_read_b128 v[132:135], v178 offset:23552
	s_waitcnt lgkmcnt(8)
	v_mfma_f32_16x16x32_bf16 v[76:79], v[146:149], v[0:3], 0
	v_mfma_f32_16x16x32_bf16 v[76:79], v[150:153], v[4:7], v[76:79]
	v_mfma_f32_16x16x32_bf16 v[76:79], v[154:157], v[8:11], v[76:79]
	v_mfma_f32_16x16x32_bf16 v[76:79], v[158:161], v[12:15], v[76:79]
	v_mfma_f32_16x16x32_bf16 v[76:79], v[162:165], v[16:19], v[76:79]
	v_mfma_f32_16x16x32_bf16 v[76:79], v[166:169], v[20:23], v[76:79]
	v_mfma_f32_16x16x32_bf16 v[76:79], v[170:173], v[24:27], v[76:79]
	v_mfma_f32_16x16x32_bf16 v[76:79], v[174:177], v[28:31], v[76:79]
	s_waitcnt vmcnt(1)
	s_barrier
	s_add_i32 m0, s7, 8192
	s_nop 0
	global_load_lds_dwordx4 v[180:181], off
	v_lshl_add_u64 v[180:181], v[180:181], 0, s[98:99]
	ds_read_b128 v[146:149], v178 offset:24576
	ds_read_b128 v[150:153], v178 offset:25600
	ds_read_b128 v[154:157], v178 offset:26624
	ds_read_b128 v[158:161], v178 offset:27648
	ds_read_b128 v[162:165], v178 offset:28672
	ds_read_b128 v[166:169], v178 offset:29696
	ds_read_b128 v[170:173], v178 offset:30720
	ds_read_b128 v[174:177], v178 offset:31744
	s_waitcnt lgkmcnt(8)
	v_mfma_f32_16x16x32_bf16 v[80:83], v[104:107], v[0:3], 0
	v_mfma_f32_16x16x32_bf16 v[80:83], v[108:111], v[4:7], v[80:83]
	v_mfma_f32_16x16x32_bf16 v[80:83], v[112:115], v[8:11], v[80:83]
	v_mfma_f32_16x16x32_bf16 v[80:83], v[116:119], v[12:15], v[80:83]
	v_mfma_f32_16x16x32_bf16 v[80:83], v[120:123], v[16:19], v[80:83]
	v_mfma_f32_16x16x32_bf16 v[80:83], v[124:127], v[20:23], v[80:83]
	v_mfma_f32_16x16x32_bf16 v[80:83], v[128:131], v[24:27], v[80:83]
	v_mfma_f32_16x16x32_bf16 v[80:83], v[132:135], v[28:31], v[80:83]
	s_waitcnt vmcnt(1)
	s_barrier
	s_add_i32 m0, s7, 16384
	s_nop 0
	global_load_lds_dwordx4 v[180:181], off
	v_lshl_add_u64 v[180:181], v[180:181], 0, s[98:99]
	ds_read_b128 v[104:107], v178 offset:0
	ds_read_b128 v[108:111], v178 offset:1024
	ds_read_b128 v[112:115], v178 offset:2048
	ds_read_b128 v[116:119], v178 offset:3072
	ds_read_b128 v[120:123], v178 offset:4096
	ds_read_b128 v[124:127], v178 offset:5120
	ds_read_b128 v[128:131], v178 offset:6144
	ds_read_b128 v[132:135], v178 offset:7168
	s_waitcnt lgkmcnt(8)
	v_mfma_f32_16x16x32_bf16 v[84:87], v[146:149], v[0:3], 0
	v_mfma_f32_16x16x32_bf16 v[84:87], v[150:153], v[4:7], v[84:87]
	v_mfma_f32_16x16x32_bf16 v[84:87], v[154:157], v[8:11], v[84:87]
	v_mfma_f32_16x16x32_bf16 v[84:87], v[158:161], v[12:15], v[84:87]
	v_mfma_f32_16x16x32_bf16 v[84:87], v[162:165], v[16:19], v[84:87]
	v_mfma_f32_16x16x32_bf16 v[84:87], v[166:169], v[20:23], v[84:87]
	v_mfma_f32_16x16x32_bf16 v[84:87], v[170:173], v[24:27], v[84:87]
	v_mfma_f32_16x16x32_bf16 v[84:87], v[174:177], v[28:31], v[84:87]
	s_waitcnt vmcnt(1)
	s_barrier
; __device__ __forceinline__ f32x4 mfma16(bf16x8 a, bf16x8 b, f32x4 c) { return __builtin_amdgcn_mfma_f32_16x16x32_bf16(a, b, c, 0, 0, 0); }
; __device__ __forceinline__ void mem_task(bf16_t* zb, const bf16_t* kvm_b, const bf16_t* vmt_b, int hm, int t0, int lane, bool do_store) {
;     ...
;     for (int kt = 0; kt < 16; ++kt) {
;         if (kt + 2 < 16) { const bf16_t* kp = kbase + (size_t)(((kt + 2) >> 1) * 32 + 4 * ((kt + 2) & 1)) * 2048;
; #pragma unroll
;             for (int kk = 0; kk < 8; ++kk) kfr[(kt + 2) % 3][kk] = *(const bf16x8*)(kp + kk * 32); }
;         f32x4 acc = zero4;
;         __builtin_amdgcn_s_setprio(1);
; #pragma unroll
;         for (int kk = 0; kk < 8; ++kk) acc = mfma16(kfr[kt % 3][kk], qf[kk], acc);
;         __builtin_amdgcn_s_setprio(0);
;         s[kt] = acc; }
;     float l = 0.f;
; #pragma unroll
;     for (int kt = 0; kt < 16; ++kt)
; #pragma unroll
;         for (int j = 0; j < 4; ++j) { s[kt][j] = __builtin_amdgcn_exp2f(s[kt][j]); l += s[kt][j]; }
	s_add_i32 m0, s7, 24576
	s_nop 0
	global_load_lds_dwordx4 v[180:181], off
	v_lshl_add_u64 v[180:181], v[180:181], 0, s[98:99]
	ds_read_b128 v[146:149], v178 offset:8192
	ds_read_b128 v[150:153], v178 offset:9216
	ds_read_b128 v[154:157], v178 offset:10240
	ds_read_b128 v[158:161], v178 offset:11264
	ds_read_b128 v[162:165], v178 offset:12288
	ds_read_b128 v[166:169], v178 offset:13312
	ds_read_b128 v[170:173], v178 offset:14336
	ds_read_b128 v[174:177], v178 offset:15360
	s_waitcnt lgkmcnt(8)
	v_mfma_f32_16x16x32_bf16 v[88:91], v[104:107], v[0:3], 0
	v_mfma_f32_16x16x32_bf16 v[88:91], v[108:111], v[4:7], v[88:91]
	v_mfma_f32_16x16x32_bf16 v[88:91], v[112:115], v[8:11], v[88:91]
	v_mfma_f32_16x16x32_bf16 v[88:91], v[116:119], v[12:15], v[88:91]
	v_mfma_f32_16x16x32_bf16 v[88:91], v[120:123], v[16:19], v[88:91]
	v_mfma_f32_16x16x32_bf16 v[88:91], v[124:127], v[20:23], v[88:91]
	v_mfma_f32_16x16x32_bf16 v[88:91], v[128:131], v[24:27], v[88:91]
	v_mfma_f32_16x16x32_bf16 v[88:91], v[132:135], v[28:31], v[88:91]
	s_waitcnt vmcnt(1)
	s_barrier
	s_add_i32 m0, s7, 0
	s_nop 0
	global_load_lds_dwordx4 v[182:183], off
	v_lshl_add_u64 v[182:183], v[182:183], 0, s[98:99]
	ds_read_b128 v[104:107], v178 offset:16384
	ds_read_b128 v[108:111], v178 offset:17408
	ds_read_b128 v[112:115], v178 offset:18432
	ds_read_b128 v[116:119], v178 offset:19456
	ds_read_b128 v[120:123], v178 offset:20480
	ds_read_b128 v[124:127], v178 offset:21504
	ds_read_b128 v[128:131], v178 offset:22528
	ds_read_b128 v[132:135], v178 offset:23552
	s_waitcnt lgkmcnt(8)
	v_mfma_f32_16x16x32_bf16 v[92:95], v[146:149], v[0:3], 0
	v_mfma_f32_16x16x32_bf16 v[92:95], v[150:153], v[4:7], v[92:95]
	v_mfma_f32_16x16x32_bf16 v[92:95], v[154:157], v[8:11], v[92:95]
	v_mfma_f32_16x16x32_bf16 v[92:95], v[158:161], v[12:15], v[92:95]
	v_mfma_f32_16x16x32_bf16 v[92:95], v[162:165], v[16:19], v[92:95]
	v_mfma_f32_16x16x32_bf16 v[92:95], v[166:169], v[20:23], v[92:95]
	v_mfma_f32_16x16x32_bf16 v[92:95], v[170:173], v[24:27], v[92:95]
	v_mfma_f32_16x16x32_bf16 v[92:95], v[174:177], v[28:31], v[92:95]
	s_waitcnt vmcnt(1)
	s_barrier
	s_add_i32 m0, s7, 8192
	s_nop 0
	global_load_lds_dwordx4 v[182:183], off
	v_lshl_add_u64 v[182:183], v[182:183], 0, s[98:99]
	ds_read_b128 v[146:149], v178 offset:24576
	ds_read_b128 v[150:153], v178 offset:25600
	ds_read_b128 v[154:157], v178 offset:26624
	ds_read_b128 v[158:161], v178 offset:27648
	ds_read_b128 v[162:165], v178 offset:28672
	ds_read_b128 v[166:169], v178 offset:29696
	ds_read_b128 v[170:173], v178 offset:30720
	ds_read_b128 v[174:177], v178 offset:31744
	s_waitcnt lgkmcnt(8)
	v_mfma_f32_16x16x32_bf16 v[96:99], v[104:107], v[0:3], 0
	v_mfma_f32_16x16x32_bf16 v[96:99], v[108:111], v[4:7], v[96:99]
	v_mfma_f32_16x16x32_bf16 v[96:99], v[112:115], v[8:11], v[96:99]
	v_mfma_f32_16x16x32_bf16 v[96:99], v[116:119], v[12:15], v[96:99]
	v_mfma_f32_16x16x32_bf16 v[96:99], v[120:123], v[16:19], v[96:99]
	v_mfma_f32_16x16x32_bf16 v[96:99], v[124:127], v[20:23], v[96:99]
	v_mfma_f32_16x16x32_bf16 v[96:99], v[128:131], v[24:27], v[96:99]
	v_mfma_f32_16x16x32_bf16 v[96:99], v[132:135], v[28:31], v[96:99]
	s_waitcnt vmcnt(1)
	s_barrier
	s_add_i32 m0, s7, 16384
	s_nop 0
	global_load_lds_dwordx4 v[182:183], off
	v_lshl_add_u64 v[182:183], v[182:183], 0, s[98:99]
	ds_read_b128 v[104:107], v178 offset:0
	ds_read_b128 v[108:111], v178 offset:1024
	ds_read_b128 v[112:115], v178 offset:2048
	ds_read_b128 v[116:119], v178 offset:3072
	ds_read_b128 v[120:123], v178 offset:4096
	ds_read_b128 v[124:127], v178 offset:5120
	ds_read_b128 v[128:131], v178 offset:6144
	ds_read_b128 v[132:135], v178 offset:7168
	s_waitcnt lgkmcnt(8)
	v_mfma_f32_16x16x32_bf16 v[100:103], v[146:149], v[0:3], 0
	v_mfma_f32_16x16x32_bf16 v[100:103], v[150:153], v[4:7], v[100:103]
	v_mfma_f32_16x16x32_bf16 v[100:103], v[154:157], v[8:11], v[100:103]
	v_mfma_f32_16x16x32_bf16 v[100:103], v[158:161], v[12:15], v[100:103]
	v_mfma_f32_16x16x32_bf16 v[100:103], v[162:165], v[16:19], v[100:103]
	v_mfma_f32_16x16x32_bf16 v[100:103], v[166:169], v[20:23], v[100:103]
	v_mfma_f32_16x16x32_bf16 v[100:103], v[170:173], v[24:27], v[100:103]
	v_mfma_f32_16x16x32_bf16 v[100:103], v[174:177], v[28:31], v[100:103]
	s_nop 7
	s_nop 7
	v_exp_f32_e32 v32, v32
	v_exp_f32_e32 v33, v33
	v_add_f32_e32 v190, 0, v32
	v_exp_f32_e32 v34, v34
	v_add_f32_e32 v190, v190, v33
	v_exp_f32_e32 v35, v35
	v_add_f32_e32 v190, v190, v34
	v_exp_f32_e32 v36, v36
	v_add_f32_e32 v190, v190, v35
	v_exp_f32_e32 v37, v37
	v_add_f32_e32 v190, v190, v36
	v_exp_f32_e32 v38, v38
	v_add_f32_e32 v190, v190, v37
	v_exp_f32_e32 v39, v39
	v_add_f32_e32 v190, v190, v38
	v_exp_f32_e32 v40, v40
	v_add_f32_e32 v190, v190, v39
	v_exp_f32_e32 v41, v41
	v_add_f32_e32 v190, v190, v40
	v_exp_f32_e32 v42, v42
	v_add_f32_e32 v190, v190, v41
	v_exp_f32_e32 v43, v43
	v_add_f32_e32 v190, v190, v42
	v_exp_f32_e32 v44, v44
	v_add_f32_e32 v190, v190, v43
	v_exp_f32_e32 v45, v45
	v_add_f32_e32 v190, v190, v44
	v_exp_f32_e32 v46, v46
	v_add_f32_e32 v190, v190, v45
	v_exp_f32_e32 v47, v47
	v_add_f32_e32 v190, v190, v46
	v_exp_f32_e32 v48, v48
	v_add_f32_e32 v190, v190, v47
	v_exp_f32_e32 v49, v49
	v_add_f32_e32 v190, v190, v48
	v_exp_f32_e32 v50, v50
	v_add_f32_e32 v190, v190, v49
	v_exp_f32_e32 v51, v51
	v_add_f32_e32 v190, v190, v50
	v_exp_f32_e32 v52, v52
	v_add_f32_e32 v190, v190, v51
	v_exp_f32_e32 v53, v53
	v_add_f32_e32 v190, v190, v52
	v_exp_f32_e32 v54, v54
	v_add_f32_e32 v190, v190, v53
	v_exp_f32_e32 v55, v55
	v_add_f32_e32 v190, v190, v54
	v_exp_f32_e32 v56, v56
	v_add_f32_e32 v190, v190, v55
	v_exp_f32_e32 v57, v57
	v_add_f32_e32 v190, v190, v56
	v_exp_f32_e32 v58, v58
; __device__ __forceinline__ unsigned cvt_pk_bf16(float lo, float hi) { unsigned r; asm volatile("v_cvt_pk_bf16_f32 %0, %1, %2" : "=v"(r) : "v"(lo), "v"(hi)); return r; }
; __device__ __forceinline__ f32x4 mfma16(bf16x8 a, bf16x8 b, f32x4 c) { return __builtin_amdgcn_mfma_f32_16x16x32_bf16(a, b, c, 0, 0, 0); }
; __device__ __forceinline__ float x16sum(float x) { auto r = __builtin_amdgcn_permlane16_swap(__float_as_uint(x), __float_as_uint(x), false, false); return __uint_as_float(r[0]) + __uint_as_float(r[1]); }
; __device__ __forceinline__ void mem_task(bf16_t* zb, const bf16_t* kvm_b, const bf16_t* vmt_b, int hm, int t0, int lane, bool do_store) {
;     ...
;     for (int kt = 0; kt < 16; ++kt)
; #pragma unroll
;         for (int j = 0; j < 4; ++j) { s[kt][j] = __builtin_amdgcn_exp2f(s[kt][j]); l += s[kt][j]; }
;     l = x16sum(l); l = x32sum(l);
;     const float il = 1.0f / l;
;     bf16x8 pf[8];
; #pragma unroll
;     for (int kp = 0; kp < 8; ++kp) { u32x4 w; w.x = cvt_pk_bf16(s[2 * kp][0], s[2 * kp][1]); w.y = cvt_pk_bf16(s[2 * kp][2], s[2 * kp][3]); w.z = cvt_pk_bf16(s[2 * kp + 1][0], s[2 * kp + 1][1]); w.w = cvt_pk_bf16(s[2 * kp + 1][2], s[2 * kp + 1][3]); pf[kp] = __builtin_bit_cast(bf16x8, w); }
;     const bf16_t* vbase = vmt_b + (size_t)(hm * 256 + n) * 256 + 8 * fq;
;     bf16x8 vfr[3][8];
; #pragma unroll
;     for (int kp = 0; kp < 8; ++kp) vfr[0][kp] = *(const bf16x8*)(vbase + kp * 32);
;     { const bf16_t* vp = vbase + (size_t)16 * 256;
; #pragma unroll
;       for (int kp = 0; kp < 8; ++kp) vfr[1][kp] = *(const bf16x8*)(vp + kp * 32); }
; #pragma unroll
;     for (int dt = 0; dt < 16; ++dt) {
;         if (dt + 2 < 16) { const bf16_t* vp = vbase + (size_t)((dt + 2) * 16) * 256;
; #pragma unroll
;             for (int kp = 0; kp < 8; ++kp) vfr[(dt + 2) % 3][kp] = *(const bf16x8*)(vp + kp * 32); }
;         f32x4 acc = zero4;
;         __builtin_amdgcn_s_setprio(1);
; #pragma unroll
;         for (int kp = 0; kp < 8; ++kp) acc = mfma16(vfr[dt % 3][kp], pf[kp], acc);
;         __builtin_amdgcn_s_setprio(0);
;         u32x2 w; w.x = cvt_pk_bf16(acc[0] * il, acc[1] * il); w.y = cvt_pk_bf16(acc[2] * il, acc[3] * il); if (do_store || acc[0] == 12345.678f) *(u32x2*)(qp + dt * 16 + 4 * fq) = w; }
	v_add_f32_e32 v190, v190, v57
	v_exp_f32_e32 v59, v59
	v_add_f32_e32 v190, v190, v58
	v_exp_f32_e32 v60, v60
	v_add_f32_e32 v190, v190, v59
	v_exp_f32_e32 v61, v61
	v_add_f32_e32 v190, v190, v60
	v_exp_f32_e32 v62, v62
	v_add_f32_e32 v190, v190, v61
	v_exp_f32_e32 v63, v63
	v_add_f32_e32 v190, v190, v62
	v_exp_f32_e32 v72, v72
	v_add_f32_e32 v190, v190, v63
	v_exp_f32_e32 v73, v73
	v_add_f32_e32 v190, v190, v72
	v_exp_f32_e32 v74, v74
	v_add_f32_e32 v190, v190, v73
	v_exp_f32_e32 v75, v75
	v_add_f32_e32 v190, v190, v74
	v_exp_f32_e32 v76, v76
	v_add_f32_e32 v190, v190, v75
	v_exp_f32_e32 v77, v77
	v_add_f32_e32 v190, v190, v76
	v_exp_f32_e32 v78, v78
	v_add_f32_e32 v190, v190, v77
	v_exp_f32_e32 v79, v79
	v_add_f32_e32 v190, v190, v78
	v_exp_f32_e32 v80, v80
	v_add_f32_e32 v190, v190, v79
	v_exp_f32_e32 v81, v81
	v_add_f32_e32 v190, v190, v80
	v_exp_f32_e32 v82, v82
	v_add_f32_e32 v190, v190, v81
	v_exp_f32_e32 v83, v83
	v_add_f32_e32 v190, v190, v82
	v_exp_f32_e32 v84, v84
	v_add_f32_e32 v190, v190, v83
	v_exp_f32_e32 v85, v85
	v_add_f32_e32 v190, v190, v84
	v_exp_f32_e32 v86, v86
	v_add_f32_e32 v190, v190, v85
	v_exp_f32_e32 v87, v87
	v_add_f32_e32 v190, v190, v86
	v_exp_f32_e32 v88, v88
	v_add_f32_e32 v190, v190, v87
	v_exp_f32_e32 v89, v89
	v_add_f32_e32 v190, v190, v88
	v_exp_f32_e32 v90, v90
	v_add_f32_e32 v190, v190, v89
	v_exp_f32_e32 v91, v91
	v_add_f32_e32 v190, v190, v90
	v_exp_f32_e32 v92, v92
	v_add_f32_e32 v190, v190, v91
	v_exp_f32_e32 v93, v93
	v_add_f32_e32 v190, v190, v92
	v_exp_f32_e32 v94, v94
	v_add_f32_e32 v190, v190, v93
	v_exp_f32_e32 v95, v95
	v_add_f32_e32 v190, v190, v94
	v_exp_f32_e32 v96, v96
	v_add_f32_e32 v190, v190, v95
	v_exp_f32_e32 v97, v97
	v_add_f32_e32 v190, v190, v96
	v_exp_f32_e32 v98, v98
	v_add_f32_e32 v190, v190, v97
	v_exp_f32_e32 v99, v99
	v_add_f32_e32 v190, v190, v98
	v_exp_f32_e32 v100, v100
	v_add_f32_e32 v190, v190, v99
	v_exp_f32_e32 v101, v101
	v_add_f32_e32 v190, v190, v100
	v_exp_f32_e32 v102, v102
	v_add_f32_e32 v190, v190, v101
	v_exp_f32_e32 v103, v103
	v_add_f32_e32 v190, v190, v102
	s_nop 0
	v_add_f32_e32 v190, v190, v103
	v_mov_b32_e32 v186, v190
	s_nop 1
	v_permlane16_swap_b32_e32 v190, v186
	v_add_f32_e32 v190, v190, v186
	v_mov_b32_e32 v186, v190
	s_nop 1
	v_permlane32_swap_b32_e32 v190, v186
	v_add_f32_e32 v190, v190, v186
	v_div_scale_f32 v186, s[12:13], v190, v190, 1.0
	v_rcp_f32_e32 v187, v186
	s_nop 0
	v_fma_f32 v188, -v186, v187, 1.0
	v_fmac_f32_e32 v187, v188, v187
	v_div_scale_f32 v188, vcc, 1.0, v190, 1.0
	v_mul_f32_e32 v189, v188, v187
	v_fma_f32 v179, -v186, v189, v188
	v_fmac_f32_e32 v189, v179, v187
	v_fma_f32 v186, -v186, v189, v188
	s_nop 0
	v_div_fmas_f32 v186, v186, v187, v189
	v_div_fixup_f32 v191, v186, v190, 1.0
	v_cvt_pk_bf16_f32 v32, v32, v33
	v_cvt_pk_bf16_f32 v33, v34, v35
	v_cvt_pk_bf16_f32 v34, v36, v37
	v_cvt_pk_bf16_f32 v35, v38, v39
	v_cvt_pk_bf16_f32 v40, v40, v41
	v_cvt_pk_bf16_f32 v41, v42, v43
	v_cvt_pk_bf16_f32 v42, v44, v45
	v_cvt_pk_bf16_f32 v43, v46, v47
	v_cvt_pk_bf16_f32 v48, v48, v49
	v_cvt_pk_bf16_f32 v49, v50, v51
	v_cvt_pk_bf16_f32 v50, v52, v53
	v_cvt_pk_bf16_f32 v51, v54, v55
	v_cvt_pk_bf16_f32 v56, v56, v57
	v_cvt_pk_bf16_f32 v57, v58, v59
	v_cvt_pk_bf16_f32 v58, v60, v61
	v_cvt_pk_bf16_f32 v59, v62, v63
	v_cvt_pk_bf16_f32 v72, v72, v73
	v_cvt_pk_bf16_f32 v73, v74, v75
	v_cvt_pk_bf16_f32 v74, v76, v77
	v_cvt_pk_bf16_f32 v75, v78, v79
	v_cvt_pk_bf16_f32 v80, v80, v81
	v_cvt_pk_bf16_f32 v81, v82, v83
	v_cvt_pk_bf16_f32 v82, v84, v85
	v_cvt_pk_bf16_f32 v83, v86, v87
	v_cvt_pk_bf16_f32 v88, v88, v89
	v_cvt_pk_bf16_f32 v89, v90, v91
	v_cvt_pk_bf16_f32 v90, v92, v93
	v_cvt_pk_bf16_f32 v91, v94, v95
	v_cvt_pk_bf16_f32 v96, v96, v97
	v_cvt_pk_bf16_f32 v97, v98, v99
	v_cvt_pk_bf16_f32 v98, v100, v101
	v_cvt_pk_bf16_f32 v99, v102, v103
	s_waitcnt vmcnt(1)
	s_barrier
	s_add_i32 m0, s7, 24576
	s_nop 0
	global_load_lds_dwordx4 v[182:183], off
	v_lshl_add_u64 v[182:183], v[182:183], 0, s[98:99]
	ds_read_b128 v[146:149], v178 offset:8192
	ds_read_b128 v[150:153], v178 offset:9216
	ds_read_b128 v[154:157], v178 offset:10240
	ds_read_b128 v[158:161], v178 offset:11264
	ds_read_b128 v[162:165], v178 offset:12288
	ds_read_b128 v[166:169], v178 offset:13312
	ds_read_b128 v[170:173], v178 offset:14336
	ds_read_b128 v[174:177], v178 offset:15360
	s_waitcnt lgkmcnt(8)
	v_mfma_f32_16x16x32_bf16 v[192:195], v[104:107], v[32:35], 0
	v_mfma_f32_16x16x32_bf16 v[192:195], v[108:111], v[40:43], v[192:195]
	v_mfma_f32_16x16x32_bf16 v[192:195], v[112:115], v[48:51], v[192:195]
	v_mfma_f32_16x16x32_bf16 v[192:195], v[116:119], v[56:59], v[192:195]
	v_mfma_f32_16x16x32_bf16 v[192:195], v[120:123], v[72:75], v[192:195]
	v_mfma_f32_16x16x32_bf16 v[192:195], v[124:127], v[80:83], v[192:195]
	v_mfma_f32_16x16x32_bf16 v[192:195], v[128:131], v[88:91], v[192:195]
	v_mfma_f32_16x16x32_bf16 v[192:195], v[132:135], v[96:99], v[192:195]
	s_waitcnt vmcnt(1)
	s_barrier
	s_add_i32 m0, s7, 0
	s_nop 0
	global_load_lds_dwordx4 v[182:183], off
	v_lshl_add_u64 v[182:183], v[182:183], 0, s[98:99]
	ds_read_b128 v[104:107], v178 offset:16384
	ds_read_b128 v[108:111], v178 offset:17408
	ds_read_b128 v[112:115], v178 offset:18432
	ds_read_b128 v[116:119], v178 offset:19456
	ds_read_b128 v[120:123], v178 offset:20480
	ds_read_b128 v[124:127], v178 offset:21504
	ds_read_b128 v[128:131], v178 offset:22528
	ds_read_b128 v[132:135], v178 offset:23552
	s_waitcnt lgkmcnt(8)
	v_mfma_f32_16x16x32_bf16 v[196:199], v[146:149], v[32:35], 0
	v_mfma_f32_16x16x32_bf16 v[196:199], v[150:153], v[40:43], v[196:199]
	v_mfma_f32_16x16x32_bf16 v[196:199], v[154:157], v[48:51], v[196:199]
	v_mfma_f32_16x16x32_bf16 v[196:199], v[158:161], v[56:59], v[196:199]
	v_mfma_f32_16x16x32_bf16 v[196:199], v[162:165], v[72:75], v[196:199]
	v_mfma_f32_16x16x32_bf16 v[196:199], v[166:169], v[80:83], v[196:199]
	v_mfma_f32_16x16x32_bf16 v[196:199], v[170:173], v[88:91], v[196:199]
	v_mfma_f32_16x16x32_bf16 v[196:199], v[174:177], v[96:99], v[196:199]
	v_mul_f32_e32 v192, v191, v192
	v_mul_f32_e32 v193, v191, v193
	v_mul_f32_e32 v194, v191, v194
	v_mul_f32_e32 v195, v191, v195
	v_cvt_pk_bf16_f32 v192, v192, v193
	v_cvt_pk_bf16_f32 v193, v194, v195
	global_store_dwordx2 v[184:185], v[192:193], off
	s_waitcnt vmcnt(2)
	s_barrier
; __device__ __forceinline__ unsigned cvt_pk_bf16(float lo, float hi) { unsigned r; asm volatile("v_cvt_pk_bf16_f32 %0, %1, %2" : "=v"(r) : "v"(lo), "v"(hi)); return r; }
; __device__ __forceinline__ f32x4 mfma16(bf16x8 a, bf16x8 b, f32x4 c) { return __builtin_amdgcn_mfma_f32_16x16x32_bf16(a, b, c, 0, 0, 0); }
; __device__ __forceinline__ void mem_task(bf16_t* zb, const bf16_t* kvm_b, const bf16_t* vmt_b, int hm, int t0, int lane, bool do_store) {
;     ...
;     for (int dt = 0; dt < 16; ++dt) {
;         if (dt + 2 < 16) { const bf16_t* vp = vbase + (size_t)((dt + 2) * 16) * 256;
; #pragma unroll
;             for (int kp = 0; kp < 8; ++kp) vfr[(dt + 2) % 3][kp] = *(const bf16x8*)(vp + kp * 32); }
;         f32x4 acc = zero4;
;         __builtin_amdgcn_s_setprio(1);
; #pragma unroll
;         for (int kp = 0; kp < 8; ++kp) acc = mfma16(vfr[dt % 3][kp], pf[kp], acc);
;         __builtin_amdgcn_s_setprio(0);
;         u32x2 w; w.x = cvt_pk_bf16(acc[0] * il, acc[1] * il); w.y = cvt_pk_bf16(acc[2] * il, acc[3] * il); if (do_store || acc[0] == 12345.678f) *(u32x2*)(qp + dt * 16 + 4 * fq) = w; }
	s_add_i32 m0, s7, 8192
	s_nop 0
	global_load_lds_dwordx4 v[182:183], off
	v_lshl_add_u64 v[182:183], v[182:183], 0, s[98:99]
	ds_read_b128 v[146:149], v178 offset:24576
	ds_read_b128 v[150:153], v178 offset:25600
	ds_read_b128 v[154:157], v178 offset:26624
	ds_read_b128 v[158:161], v178 offset:27648
	ds_read_b128 v[162:165], v178 offset:28672
	ds_read_b128 v[166:169], v178 offset:29696
	ds_read_b128 v[170:173], v178 offset:30720
	ds_read_b128 v[174:177], v178 offset:31744
	s_waitcnt lgkmcnt(8)
	v_mfma_f32_16x16x32_bf16 v[192:195], v[104:107], v[32:35], 0
	v_mfma_f32_16x16x32_bf16 v[192:195], v[108:111], v[40:43], v[192:195]
	v_mfma_f32_16x16x32_bf16 v[192:195], v[112:115], v[48:51], v[192:195]
	v_mfma_f32_16x16x32_bf16 v[192:195], v[116:119], v[56:59], v[192:195]
	v_mfma_f32_16x16x32_bf16 v[192:195], v[120:123], v[72:75], v[192:195]
	v_mfma_f32_16x16x32_bf16 v[192:195], v[124:127], v[80:83], v[192:195]
	v_mfma_f32_16x16x32_bf16 v[192:195], v[128:131], v[88:91], v[192:195]
	v_mfma_f32_16x16x32_bf16 v[192:195], v[132:135], v[96:99], v[192:195]
	v_mul_f32_e32 v196, v191, v196
	v_mul_f32_e32 v197, v191, v197
	v_mul_f32_e32 v198, v191, v198
	v_mul_f32_e32 v199, v191, v199
	v_cvt_pk_bf16_f32 v196, v196, v197
	v_cvt_pk_bf16_f32 v197, v198, v199
	global_store_dwordx2 v[184:185], v[196:197], off offset:32
	s_waitcnt vmcnt(3)
	s_barrier
	s_add_i32 m0, s7, 16384
	s_nop 0
	global_load_lds_dwordx4 v[182:183], off
	v_lshl_add_u64 v[182:183], v[182:183], 0, s[98:99]
	ds_read_b128 v[104:107], v178 offset:0
	ds_read_b128 v[108:111], v178 offset:1024
	ds_read_b128 v[112:115], v178 offset:2048
	ds_read_b128 v[116:119], v178 offset:3072
	ds_read_b128 v[120:123], v178 offset:4096
	ds_read_b128 v[124:127], v178 offset:5120
	ds_read_b128 v[128:131], v178 offset:6144
	ds_read_b128 v[132:135], v178 offset:7168
	s_waitcnt lgkmcnt(8)
	v_mfma_f32_16x16x32_bf16 v[196:199], v[146:149], v[32:35], 0
	v_mfma_f32_16x16x32_bf16 v[196:199], v[150:153], v[40:43], v[196:199]
	v_mfma_f32_16x16x32_bf16 v[196:199], v[154:157], v[48:51], v[196:199]
	v_mfma_f32_16x16x32_bf16 v[196:199], v[158:161], v[56:59], v[196:199]
	v_mfma_f32_16x16x32_bf16 v[196:199], v[162:165], v[72:75], v[196:199]
	v_mfma_f32_16x16x32_bf16 v[196:199], v[166:169], v[80:83], v[196:199]
	v_mfma_f32_16x16x32_bf16 v[196:199], v[170:173], v[88:91], v[196:199]
	v_mfma_f32_16x16x32_bf16 v[196:199], v[174:177], v[96:99], v[196:199]
	v_mul_f32_e32 v192, v191, v192
	v_mul_f32_e32 v193, v191, v193
	v_mul_f32_e32 v194, v191, v194
	v_mul_f32_e32 v195, v191, v195
	v_cvt_pk_bf16_f32 v192, v192, v193
	v_cvt_pk_bf16_f32 v193, v194, v195
	global_store_dwordx2 v[184:185], v[192:193], off offset:64
	s_waitcnt vmcnt(3)
	s_barrier
	s_add_i32 m0, s7, 24576
	s_nop 0
	global_load_lds_dwordx4 v[182:183], off
	v_lshl_add_u64 v[182:183], v[182:183], 0, s[98:99]
	ds_read_b128 v[146:149], v178 offset:8192
	ds_read_b128 v[150:153], v178 offset:9216
	ds_read_b128 v[154:157], v178 offset:10240
	ds_read_b128 v[158:161], v178 offset:11264
	ds_read_b128 v[162:165], v178 offset:12288
	ds_read_b128 v[166:169], v178 offset:13312
	ds_read_b128 v[170:173], v178 offset:14336
	ds_read_b128 v[174:177], v178 offset:15360
	s_waitcnt lgkmcnt(8)
	v_mfma_f32_16x16x32_bf16 v[192:195], v[104:107], v[32:35], 0
	v_mfma_f32_16x16x32_bf16 v[192:195], v[108:111], v[40:43], v[192:195]
	v_mfma_f32_16x16x32_bf16 v[192:195], v[112:115], v[48:51], v[192:195]
	v_mfma_f32_16x16x32_bf16 v[192:195], v[116:119], v[56:59], v[192:195]
	v_mfma_f32_16x16x32_bf16 v[192:195], v[120:123], v[72:75], v[192:195]
	v_mfma_f32_16x16x32_bf16 v[192:195], v[124:127], v[80:83], v[192:195]
	v_mfma_f32_16x16x32_bf16 v[192:195], v[128:131], v[88:91], v[192:195]
	v_mfma_f32_16x16x32_bf16 v[192:195], v[132:135], v[96:99], v[192:195]
	v_mul_f32_e32 v196, v191, v196
	v_mul_f32_e32 v197, v191, v197
	v_mul_f32_e32 v198, v191, v198
	v_mul_f32_e32 v199, v191, v199
	v_cvt_pk_bf16_f32 v196, v196, v197
	v_cvt_pk_bf16_f32 v197, v198, v199
	global_store_dwordx2 v[184:185], v[196:197], off offset:96
	s_waitcnt vmcnt(3)
	s_barrier
	s_add_i32 m0, s7, 0
	s_nop 0
	global_load_lds_dwordx4 v[182:183], off
	v_lshl_add_u64 v[182:183], v[182:183], 0, s[98:99]
	ds_read_b128 v[104:107], v178 offset:16384
	ds_read_b128 v[108:111], v178 offset:17408
	ds_read_b128 v[112:115], v178 offset:18432
	ds_read_b128 v[116:119], v178 offset:19456
	ds_read_b128 v[120:123], v178 offset:20480
	ds_read_b128 v[124:127], v178 offset:21504
	ds_read_b128 v[128:131], v178 offset:22528
	ds_read_b128 v[132:135], v178 offset:23552
	s_waitcnt lgkmcnt(8)
	v_mfma_f32_16x16x32_bf16 v[196:199], v[146:149], v[32:35], 0
	v_mfma_f32_16x16x32_bf16 v[196:199], v[150:153], v[40:43], v[196:199]
	v_mfma_f32_16x16x32_bf16 v[196:199], v[154:157], v[48:51], v[196:199]
	v_mfma_f32_16x16x32_bf16 v[196:199], v[158:161], v[56:59], v[196:199]
	v_mfma_f32_16x16x32_bf16 v[196:199], v[162:165], v[72:75], v[196:199]
	v_mfma_f32_16x16x32_bf16 v[196:199], v[166:169], v[80:83], v[196:199]
	v_mfma_f32_16x16x32_bf16 v[196:199], v[170:173], v[88:91], v[196:199]
	v_mfma_f32_16x16x32_bf16 v[196:199], v[174:177], v[96:99], v[196:199]
	v_mul_f32_e32 v192, v191, v192
	v_mul_f32_e32 v193, v191, v193
	v_mul_f32_e32 v194, v191, v194
	v_mul_f32_e32 v195, v191, v195
	v_cvt_pk_bf16_f32 v192, v192, v193
	v_cvt_pk_bf16_f32 v193, v194, v195
	global_store_dwordx2 v[184:185], v[192:193], off offset:128
	s_waitcnt vmcnt(3)
	s_barrier
; __device__ __forceinline__ unsigned cvt_pk_bf16(float lo, float hi) { unsigned r; asm volatile("v_cvt_pk_bf16_f32 %0, %1, %2" : "=v"(r) : "v"(lo), "v"(hi)); return r; }
; __device__ __forceinline__ f32x4 mfma16(bf16x8 a, bf16x8 b, f32x4 c) { return __builtin_amdgcn_mfma_f32_16x16x32_bf16(a, b, c, 0, 0, 0); }
; __device__ __forceinline__ void mem_task(bf16_t* zb, const bf16_t* kvm_b, const bf16_t* vmt_b, int hm, int t0, int lane, bool do_store) {
;     ...
;     for (int dt = 0; dt < 16; ++dt) {
;         if (dt + 2 < 16) { const bf16_t* vp = vbase + (size_t)((dt + 2) * 16) * 256;
; #pragma unroll
;             for (int kp = 0; kp < 8; ++kp) vfr[(dt + 2) % 3][kp] = *(const bf16x8*)(vp + kp * 32); }
;         f32x4 acc = zero4;
;         __builtin_amdgcn_s_setprio(1);
; #pragma unroll
;         for (int kp = 0; kp < 8; ++kp) acc = mfma16(vfr[dt % 3][kp], pf[kp], acc);
;         __builtin_amdgcn_s_setprio(0);
;         u32x2 w; w.x = cvt_pk_bf16(acc[0] * il, acc[1] * il); w.y = cvt_pk_bf16(acc[2] * il, acc[3] * il); if (do_store || acc[0] == 12345.678f) *(u32x2*)(qp + dt * 16 + 4 * fq) = w; }
	s_add_i32 m0, s7, 8192
	s_nop 0
	global_load_lds_dwordx4 v[182:183], off
	v_lshl_add_u64 v[182:183], v[182:183], 0, s[98:99]
	ds_read_b128 v[146:149], v178 offset:24576
	ds_read_b128 v[150:153], v178 offset:25600
	ds_read_b128 v[154:157], v178 offset:26624
	ds_read_b128 v[158:161], v178 offset:27648
	ds_read_b128 v[162:165], v178 offset:28672
	ds_read_b128 v[166:169], v178 offset:29696
	ds_read_b128 v[170:173], v178 offset:30720
	ds_read_b128 v[174:177], v178 offset:31744
	s_waitcnt lgkmcnt(8)
	v_mfma_f32_16x16x32_bf16 v[192:195], v[104:107], v[32:35], 0
	v_mfma_f32_16x16x32_bf16 v[192:195], v[108:111], v[40:43], v[192:195]
	v_mfma_f32_16x16x32_bf16 v[192:195], v[112:115], v[48:51], v[192:195]
	v_mfma_f32_16x16x32_bf16 v[192:195], v[116:119], v[56:59], v[192:195]
	v_mfma_f32_16x16x32_bf16 v[192:195], v[120:123], v[72:75], v[192:195]
	v_mfma_f32_16x16x32_bf16 v[192:195], v[124:127], v[80:83], v[192:195]
	v_mfma_f32_16x16x32_bf16 v[192:195], v[128:131], v[88:91], v[192:195]
	v_mfma_f32_16x16x32_bf16 v[192:195], v[132:135], v[96:99], v[192:195]
	v_mul_f32_e32 v196, v191, v196
	v_mul_f32_e32 v197, v191, v197
	v_mul_f32_e32 v198, v191, v198
	v_mul_f32_e32 v199, v191, v199
	v_cvt_pk_bf16_f32 v196, v196, v197
	v_cvt_pk_bf16_f32 v197, v198, v199
	global_store_dwordx2 v[184:185], v[196:197], off offset:160
	s_waitcnt vmcnt(3)
	s_barrier
	s_add_i32 m0, s7, 16384
	s_nop 0
	global_load_lds_dwordx4 v[182:183], off
	v_lshl_add_u64 v[182:183], v[182:183], 0, s[98:99]
	ds_read_b128 v[104:107], v178 offset:0
	ds_read_b128 v[108:111], v178 offset:1024
	ds_read_b128 v[112:115], v178 offset:2048
	ds_read_b128 v[116:119], v178 offset:3072
	ds_read_b128 v[120:123], v178 offset:4096
	ds_read_b128 v[124:127], v178 offset:5120
	ds_read_b128 v[128:131], v178 offset:6144
	ds_read_b128 v[132:135], v178 offset:7168
	s_waitcnt lgkmcnt(8)
	v_mfma_f32_16x16x32_bf16 v[196:199], v[146:149], v[32:35], 0
	v_mfma_f32_16x16x32_bf16 v[196:199], v[150:153], v[40:43], v[196:199]
	v_mfma_f32_16x16x32_bf16 v[196:199], v[154:157], v[48:51], v[196:199]
	v_mfma_f32_16x16x32_bf16 v[196:199], v[158:161], v[56:59], v[196:199]
	v_mfma_f32_16x16x32_bf16 v[196:199], v[162:165], v[72:75], v[196:199]
	v_mfma_f32_16x16x32_bf16 v[196:199], v[166:169], v[80:83], v[196:199]
	v_mfma_f32_16x16x32_bf16 v[196:199], v[170:173], v[88:91], v[196:199]
	v_mfma_f32_16x16x32_bf16 v[196:199], v[174:177], v[96:99], v[196:199]
	v_mul_f32_e32 v192, v191, v192
	v_mul_f32_e32 v193, v191, v193
	v_mul_f32_e32 v194, v191, v194
	v_mul_f32_e32 v195, v191, v195
	v_cvt_pk_bf16_f32 v192, v192, v193
	v_cvt_pk_bf16_f32 v193, v194, v195
	global_store_dwordx2 v[184:185], v[192:193], off offset:192
	s_waitcnt vmcnt(3)
	s_barrier
	s_add_i32 m0, s7, 24576
	s_nop 0
	global_load_lds_dwordx4 v[182:183], off
	v_lshl_add_u64 v[182:183], v[182:183], 0, s[98:99]
	ds_read_b128 v[146:149], v178 offset:8192
	ds_read_b128 v[150:153], v178 offset:9216
	ds_read_b128 v[154:157], v178 offset:10240
	ds_read_b128 v[158:161], v178 offset:11264
	ds_read_b128 v[162:165], v178 offset:12288
	ds_read_b128 v[166:169], v178 offset:13312
	ds_read_b128 v[170:173], v178 offset:14336
	ds_read_b128 v[174:177], v178 offset:15360
	s_waitcnt lgkmcnt(8)
	v_mfma_f32_16x16x32_bf16 v[192:195], v[104:107], v[32:35], 0
	v_mfma_f32_16x16x32_bf16 v[192:195], v[108:111], v[40:43], v[192:195]
	v_mfma_f32_16x16x32_bf16 v[192:195], v[112:115], v[48:51], v[192:195]
	v_mfma_f32_16x16x32_bf16 v[192:195], v[116:119], v[56:59], v[192:195]
	v_mfma_f32_16x16x32_bf16 v[192:195], v[120:123], v[72:75], v[192:195]
	v_mfma_f32_16x16x32_bf16 v[192:195], v[124:127], v[80:83], v[192:195]
	v_mfma_f32_16x16x32_bf16 v[192:195], v[128:131], v[88:91], v[192:195]
	v_mfma_f32_16x16x32_bf16 v[192:195], v[132:135], v[96:99], v[192:195]
	v_mul_f32_e32 v196, v191, v196
	v_mul_f32_e32 v197, v191, v197
	v_mul_f32_e32 v198, v191, v198
	v_mul_f32_e32 v199, v191, v199
	v_cvt_pk_bf16_f32 v196, v196, v197
	v_cvt_pk_bf16_f32 v197, v198, v199
	global_store_dwordx2 v[184:185], v[196:197], off offset:224
	s_waitcnt vmcnt(3)
	s_barrier
	s_add_i32 m0, s7, 0
	s_nop 0
	global_load_lds_dwordx4 v[182:183], off
	v_lshl_add_u64 v[182:183], v[182:183], 0, s[98:99]
	ds_read_b128 v[104:107], v178 offset:16384
	ds_read_b128 v[108:111], v178 offset:17408
	ds_read_b128 v[112:115], v178 offset:18432
	ds_read_b128 v[116:119], v178 offset:19456
	ds_read_b128 v[120:123], v178 offset:20480
	ds_read_b128 v[124:127], v178 offset:21504
	ds_read_b128 v[128:131], v178 offset:22528
	ds_read_b128 v[132:135], v178 offset:23552
	s_waitcnt lgkmcnt(8)
	v_mfma_f32_16x16x32_bf16 v[196:199], v[146:149], v[32:35], 0
	v_mfma_f32_16x16x32_bf16 v[196:199], v[150:153], v[40:43], v[196:199]
	v_mfma_f32_16x16x32_bf16 v[196:199], v[154:157], v[48:51], v[196:199]
	v_mfma_f32_16x16x32_bf16 v[196:199], v[158:161], v[56:59], v[196:199]
	v_mfma_f32_16x16x32_bf16 v[196:199], v[162:165], v[72:75], v[196:199]
	v_mfma_f32_16x16x32_bf16 v[196:199], v[166:169], v[80:83], v[196:199]
	v_mfma_f32_16x16x32_bf16 v[196:199], v[170:173], v[88:91], v[196:199]
	v_mfma_f32_16x16x32_bf16 v[196:199], v[174:177], v[96:99], v[196:199]
	v_mul_f32_e32 v192, v191, v192
	v_mul_f32_e32 v193, v191, v193
	v_mul_f32_e32 v194, v191, v194
	v_mul_f32_e32 v195, v191, v195
	v_cvt_pk_bf16_f32 v192, v192, v193
	v_cvt_pk_bf16_f32 v193, v194, v195
	global_store_dwordx2 v[184:185], v[192:193], off offset:256
	s_waitcnt vmcnt(3)
	s_barrier
; __device__ __forceinline__ unsigned cvt_pk_bf16(float lo, float hi) { unsigned r; asm volatile("v_cvt_pk_bf16_f32 %0, %1, %2" : "=v"(r) : "v"(lo), "v"(hi)); return r; }
; __device__ __forceinline__ f32x4 mfma16(bf16x8 a, bf16x8 b, f32x4 c) { return __builtin_amdgcn_mfma_f32_16x16x32_bf16(a, b, c, 0, 0, 0); }
; __device__ __forceinline__ void mem_task(bf16_t* zb, const bf16_t* kvm_b, const bf16_t* vmt_b, int hm, int t0, int lane, bool do_store) {
;     ...
;     for (int dt = 0; dt < 16; ++dt) {
;         if (dt + 2 < 16) { const bf16_t* vp = vbase + (size_t)((dt + 2) * 16) * 256;
; #pragma unroll
;             for (int kp = 0; kp < 8; ++kp) vfr[(dt + 2) % 3][kp] = *(const bf16x8*)(vp + kp * 32); }
;         f32x4 acc = zero4;
;         __builtin_amdgcn_s_setprio(1);
; #pragma unroll
;         for (int kp = 0; kp < 8; ++kp) acc = mfma16(vfr[dt % 3][kp], pf[kp], acc);
;         __builtin_amdgcn_s_setprio(0);
;         u32x2 w; w.x = cvt_pk_bf16(acc[0] * il, acc[1] * il); w.y = cvt_pk_bf16(acc[2] * il, acc[3] * il); if (do_store || acc[0] == 12345.678f) *(u32x2*)(qp + dt * 16 + 4 * fq) = w; }
	s_add_i32 m0, s7, 8192
	s_nop 0
	global_load_lds_dwordx4 v[182:183], off
	v_lshl_add_u64 v[182:183], v[182:183], 0, s[98:99]
	ds_read_b128 v[146:149], v178 offset:24576
	ds_read_b128 v[150:153], v178 offset:25600
	ds_read_b128 v[154:157], v178 offset:26624
	ds_read_b128 v[158:161], v178 offset:27648
	ds_read_b128 v[162:165], v178 offset:28672
	ds_read_b128 v[166:169], v178 offset:29696
	ds_read_b128 v[170:173], v178 offset:30720
	ds_read_b128 v[174:177], v178 offset:31744
	s_waitcnt lgkmcnt(8)
	v_mfma_f32_16x16x32_bf16 v[192:195], v[104:107], v[32:35], 0
	v_mfma_f32_16x16x32_bf16 v[192:195], v[108:111], v[40:43], v[192:195]
	v_mfma_f32_16x16x32_bf16 v[192:195], v[112:115], v[48:51], v[192:195]
	v_mfma_f32_16x16x32_bf16 v[192:195], v[116:119], v[56:59], v[192:195]
	v_mfma_f32_16x16x32_bf16 v[192:195], v[120:123], v[72:75], v[192:195]
	v_mfma_f32_16x16x32_bf16 v[192:195], v[124:127], v[80:83], v[192:195]
	v_mfma_f32_16x16x32_bf16 v[192:195], v[128:131], v[88:91], v[192:195]
	v_mfma_f32_16x16x32_bf16 v[192:195], v[132:135], v[96:99], v[192:195]
	v_mul_f32_e32 v196, v191, v196
	v_mul_f32_e32 v197, v191, v197
	v_mul_f32_e32 v198, v191, v198
	v_mul_f32_e32 v199, v191, v199
	v_cvt_pk_bf16_f32 v196, v196, v197
	v_cvt_pk_bf16_f32 v197, v198, v199
	global_store_dwordx2 v[184:185], v[196:197], off offset:288
	s_waitcnt vmcnt(3)
	s_barrier
	s_add_i32 m0, s7, 16384
	s_nop 0
	global_load_lds_dwordx4 v[182:183], off
	v_lshl_add_u64 v[182:183], v[182:183], 0, s[98:99]
	ds_read_b128 v[104:107], v178 offset:0
	ds_read_b128 v[108:111], v178 offset:1024
	ds_read_b128 v[112:115], v178 offset:2048
	ds_read_b128 v[116:119], v178 offset:3072
	ds_read_b128 v[120:123], v178 offset:4096
	ds_read_b128 v[124:127], v178 offset:5120
	ds_read_b128 v[128:131], v178 offset:6144
	ds_read_b128 v[132:135], v178 offset:7168
	s_waitcnt lgkmcnt(8)
	v_mfma_f32_16x16x32_bf16 v[196:199], v[146:149], v[32:35], 0
	v_mfma_f32_16x16x32_bf16 v[196:199], v[150:153], v[40:43], v[196:199]
	v_mfma_f32_16x16x32_bf16 v[196:199], v[154:157], v[48:51], v[196:199]
	v_mfma_f32_16x16x32_bf16 v[196:199], v[158:161], v[56:59], v[196:199]
	v_mfma_f32_16x16x32_bf16 v[196:199], v[162:165], v[72:75], v[196:199]
	v_mfma_f32_16x16x32_bf16 v[196:199], v[166:169], v[80:83], v[196:199]
	v_mfma_f32_16x16x32_bf16 v[196:199], v[170:173], v[88:91], v[196:199]
	v_mfma_f32_16x16x32_bf16 v[196:199], v[174:177], v[96:99], v[196:199]
	v_mul_f32_e32 v192, v191, v192
	v_mul_f32_e32 v193, v191, v193
	v_mul_f32_e32 v194, v191, v194
	v_mul_f32_e32 v195, v191, v195
	v_cvt_pk_bf16_f32 v192, v192, v193
	v_cvt_pk_bf16_f32 v193, v194, v195
	global_store_dwordx2 v[184:185], v[192:193], off offset:320
	s_waitcnt vmcnt(3)
	s_barrier
	s_add_i32 m0, s7, 24576
	s_nop 0
	global_load_lds_dwordx4 v[182:183], off
	v_lshl_add_u64 v[182:183], v[182:183], 0, s[98:99]
	ds_read_b128 v[146:149], v178 offset:8192
	ds_read_b128 v[150:153], v178 offset:9216
	ds_read_b128 v[154:157], v178 offset:10240
	ds_read_b128 v[158:161], v178 offset:11264
	ds_read_b128 v[162:165], v178 offset:12288
	ds_read_b128 v[166:169], v178 offset:13312
	ds_read_b128 v[170:173], v178 offset:14336
	ds_read_b128 v[174:177], v178 offset:15360
	s_waitcnt lgkmcnt(8)
	v_mfma_f32_16x16x32_bf16 v[192:195], v[104:107], v[32:35], 0
	v_mfma_f32_16x16x32_bf16 v[192:195], v[108:111], v[40:43], v[192:195]
	v_mfma_f32_16x16x32_bf16 v[192:195], v[112:115], v[48:51], v[192:195]
	v_mfma_f32_16x16x32_bf16 v[192:195], v[116:119], v[56:59], v[192:195]
	v_mfma_f32_16x16x32_bf16 v[192:195], v[120:123], v[72:75], v[192:195]
	v_mfma_f32_16x16x32_bf16 v[192:195], v[124:127], v[80:83], v[192:195]
	v_mfma_f32_16x16x32_bf16 v[192:195], v[128:131], v[88:91], v[192:195]
	v_mfma_f32_16x16x32_bf16 v[192:195], v[132:135], v[96:99], v[192:195]
	v_mul_f32_e32 v196, v191, v196
	v_mul_f32_e32 v197, v191, v197
	v_mul_f32_e32 v198, v191, v198
	v_mul_f32_e32 v199, v191, v199
	v_cvt_pk_bf16_f32 v196, v196, v197
	v_cvt_pk_bf16_f32 v197, v198, v199
	global_store_dwordx2 v[184:185], v[196:197], off offset:352
	s_waitcnt vmcnt(3)
	s_barrier
; __device__ __forceinline__ unsigned cvt_pk_bf16(float lo, float hi) { unsigned r; asm volatile("v_cvt_pk_bf16_f32 %0, %1, %2" : "=v"(r) : "v"(lo), "v"(hi)); return r; }
; __device__ __forceinline__ f32x4 mfma16(bf16x8 a, bf16x8 b, f32x4 c) { return __builtin_amdgcn_mfma_f32_16x16x32_bf16(a, b, c, 0, 0, 0); }
; __device__ __forceinline__ void mem_task(bf16_t* zb, const bf16_t* kvm_b, const bf16_t* vmt_b, int hm, int t0, int lane, bool do_store) {
;     ...
;     for (int dt = 0; dt < 16; ++dt) {
;         if (dt + 2 < 16) { const bf16_t* vp = vbase + (size_t)((dt + 2) * 16) * 256;
; #pragma unroll
;             for (int kp = 0; kp < 8; ++kp) vfr[(dt + 2) % 3][kp] = *(const bf16x8*)(vp + kp * 32); }
;         f32x4 acc = zero4;
;         __builtin_amdgcn_s_setprio(1);
; #pragma unroll
;         for (int kp = 0; kp < 8; ++kp) acc = mfma16(vfr[dt % 3][kp], pf[kp], acc);
;         __builtin_amdgcn_s_setprio(0);
;         u32x2 w; w.x = cvt_pk_bf16(acc[0] * il, acc[1] * il); w.y = cvt_pk_bf16(acc[2] * il, acc[3] * il); if (do_store || acc[0] == 12345.678f) *(u32x2*)(qp + dt * 16 + 4 * fq) = w; }
	ds_read_b128 v[104:107], v178 offset:16384
	ds_read_b128 v[108:111], v178 offset:17408
	ds_read_b128 v[112:115], v178 offset:18432
	ds_read_b128 v[116:119], v178 offset:19456
	ds_read_b128 v[120:123], v178 offset:20480
	ds_read_b128 v[124:127], v178 offset:21504
	ds_read_b128 v[128:131], v178 offset:22528
	ds_read_b128 v[132:135], v178 offset:23552
	s_waitcnt lgkmcnt(8)
	v_mfma_f32_16x16x32_bf16 v[196:199], v[146:149], v[32:35], 0
	v_mfma_f32_16x16x32_bf16 v[196:199], v[150:153], v[40:43], v[196:199]
	v_mfma_f32_16x16x32_bf16 v[196:199], v[154:157], v[48:51], v[196:199]
	v_mfma_f32_16x16x32_bf16 v[196:199], v[158:161], v[56:59], v[196:199]
	v_mfma_f32_16x16x32_bf16 v[196:199], v[162:165], v[72:75], v[196:199]
	v_mfma_f32_16x16x32_bf16 v[196:199], v[166:169], v[80:83], v[196:199]
	v_mfma_f32_16x16x32_bf16 v[196:199], v[170:173], v[88:91], v[196:199]
	v_mfma_f32_16x16x32_bf16 v[196:199], v[174:177], v[96:99], v[196:199]
	v_mul_f32_e32 v192, v191, v192
	v_mul_f32_e32 v193, v191, v193
	v_mul_f32_e32 v194, v191, v194
	v_mul_f32_e32 v195, v191, v195
	v_cvt_pk_bf16_f32 v192, v192, v193
	v_cvt_pk_bf16_f32 v193, v194, v195
	global_store_dwordx2 v[184:185], v[192:193], off offset:384
	s_waitcnt vmcnt(2)
	s_barrier
	ds_read_b128 v[146:149], v178 offset:24576
	ds_read_b128 v[150:153], v178 offset:25600
	ds_read_b128 v[154:157], v178 offset:26624
	ds_read_b128 v[158:161], v178 offset:27648
	ds_read_b128 v[162:165], v178 offset:28672
	ds_read_b128 v[166:169], v178 offset:29696
	ds_read_b128 v[170:173], v178 offset:30720
	ds_read_b128 v[174:177], v178 offset:31744
	s_waitcnt lgkmcnt(8)
	v_mfma_f32_16x16x32_bf16 v[192:195], v[104:107], v[32:35], 0
	v_mfma_f32_16x16x32_bf16 v[192:195], v[108:111], v[40:43], v[192:195]
	v_mfma_f32_16x16x32_bf16 v[192:195], v[112:115], v[48:51], v[192:195]
	v_mfma_f32_16x16x32_bf16 v[192:195], v[116:119], v[56:59], v[192:195]
	v_mfma_f32_16x16x32_bf16 v[192:195], v[120:123], v[72:75], v[192:195]
	v_mfma_f32_16x16x32_bf16 v[192:195], v[124:127], v[80:83], v[192:195]
	v_mfma_f32_16x16x32_bf16 v[192:195], v[128:131], v[88:91], v[192:195]
	v_mfma_f32_16x16x32_bf16 v[192:195], v[132:135], v[96:99], v[192:195]
	v_mul_f32_e32 v196, v191, v196
	v_mul_f32_e32 v197, v191, v197
	v_mul_f32_e32 v198, v191, v198
	v_mul_f32_e32 v199, v191, v199
	v_cvt_pk_bf16_f32 v196, v196, v197
	v_cvt_pk_bf16_f32 v197, v198, v199
	global_store_dwordx2 v[184:185], v[196:197], off offset:416
	s_waitcnt lgkmcnt(0)
	v_mfma_f32_16x16x32_bf16 v[196:199], v[146:149], v[32:35], 0
	v_mfma_f32_16x16x32_bf16 v[196:199], v[150:153], v[40:43], v[196:199]
	v_mfma_f32_16x16x32_bf16 v[196:199], v[154:157], v[48:51], v[196:199]
	v_mfma_f32_16x16x32_bf16 v[196:199], v[158:161], v[56:59], v[196:199]
	v_mfma_f32_16x16x32_bf16 v[196:199], v[162:165], v[72:75], v[196:199]
	v_mfma_f32_16x16x32_bf16 v[196:199], v[166:169], v[80:83], v[196:199]
	v_mfma_f32_16x16x32_bf16 v[196:199], v[170:173], v[88:91], v[196:199]
	v_mfma_f32_16x16x32_bf16 v[196:199], v[174:177], v[96:99], v[196:199]
	v_mul_f32_e32 v192, v191, v192
	v_mul_f32_e32 v193, v191, v193
	v_mul_f32_e32 v194, v191, v194
	v_mul_f32_e32 v195, v191, v195
	v_cvt_pk_bf16_f32 v192, v192, v193
	v_cvt_pk_bf16_f32 v193, v194, v195
	global_store_dwordx2 v[184:185], v[192:193], off offset:448
	s_nop 7
	s_nop 7
	v_mul_f32_e32 v196, v191, v196
	v_mul_f32_e32 v197, v191, v197
	v_mul_f32_e32 v198, v191, v198
	v_mul_f32_e32 v199, v191, v199
	v_cvt_pk_bf16_f32 v196, v196, v197
	v_cvt_pk_bf16_f32 v197, v198, v199
	global_store_dwordx2 v[184:185], v[196:197], off offset:480
	s_add_i32 s5, s5, s64
	s_cmpk_gt_i32 s5, 0x7ff
	s_cbranch_scc0 .LBB0_366
